# grid barrier: waiters poll the cross-XCD arrival counter (TOP >= (round+1)*nXCD) instead of the release generation
# speedup vs baseline: 1.0053x; 1.0006x over previous
; __device__ __forceinline__ unsigned xb_ld(unsigned* p)              { return __hip_atomic_load(p, __ATOMIC_RELAXED, __HIP_MEMORY_SCOPE_AGENT); }
; __device__ __forceinline__ unsigned xb_add(unsigned* p, unsigned v) { return __hip_atomic_fetch_add(p, v, __ATOMIC_RELAXED, __HIP_MEMORY_SCOPE_AGENT); }
; #define XB_SPIN(cond, bar) do { unsigned _sp = 0; while (cond) { __builtin_amdgcn_s_sleep(1); \
;     if ((++_sp & 255u) == 0u) { if (xb_ld(&(bar)[XB_TMO])) break; if (_sp > XB_SPIN_CAP) { atomicAdd(&(bar)[XB_TMO], 1u); break; } } } } while (0)
; __device__ __forceinline__ void xcd_barrier(const XcdBarrier& b, int wave_id) {
;     ...
;         const unsigned old = xb_add(&bar[XB_XSUB(b.x)], 1u);
;         const unsigned gen = old / nloc;
;         if (old + 1u == (gen + 1u) * nloc) {
;             __builtin_amdgcn_fence(__ATOMIC_RELEASE, "agent");
;             asm volatile("s_waitcnt vmcnt(0)" ::: "memory");
;             const unsigned og = xb_add(&bar[XB_TOP], 1u);
;             const unsigned tg = og / nx;
;             if (og + 1u == (tg + 1u) * nx) xb_add(&bar[XB_TOPGEN], 1u);
;             else XB_SPIN(xb_ld(&bar[XB_TOPGEN]) == tg, bar);
;             __builtin_amdgcn_fence(__ATOMIC_ACQUIRE, "agent");
;             xb_add(&bar[XB_XGEN(b.x)], 1u);
;             asm volatile("s_waitcnt vmcnt(0)" ::: "memory");
;         } else {
;             XB_SPIN(xb_ld(&bar[XB_XGEN(b.x)]) == gen, bar);
.LBB0_65:
	s_or_b64 exec, exec, s[18:19]
	v_cvt_f32_u32_e32 v4, v2
	s_waitcnt vmcnt(0)
	v_readfirstlane_b32 s8, v3
	v_sub_u32_e32 v3, 0, v2
	v_rcp_iflag_f32_e32 v4, v4
	v_add_u32_e32 v5, s8, v1
	v_mul_f32_e32 v4, 0x4f7ffffe, v4
	v_cvt_u32_f32_e32 v4, v4
	v_mul_lo_u32 v1, v3, v4
	v_mul_hi_u32 v1, v4, v1
	v_add_u32_e32 v1, v4, v1
	v_mul_hi_u32 v1, v5, v1
	v_mul_lo_u32 v3, v1, v2
	v_sub_u32_e32 v3, v5, v3
	v_add_u32_e32 v4, 1, v1
	v_cmp_ge_u32_e32 vcc, v3, v2
	s_nop 1
	v_cndmask_b32_e32 v1, v1, v4, vcc
	v_sub_u32_e32 v4, v3, v2
	v_cndmask_b32_e32 v3, v3, v4, vcc
	v_add_u32_e32 v4, 1, v1
	v_cmp_ge_u32_e32 vcc, v3, v2
	v_add_u32_e32 v3, 1, v5
	s_nop 0
	v_cndmask_b32_e32 v1, v1, v4, vcc
	v_mul_lo_u32 v4, v2, v1
	v_add_u32_e32 v2, v4, v2
	v_cmp_ne_u32_e32 vcc, v3, v2
	s_and_saveexec_b64 s[8:9], vcc
	s_xor_b64 s[8:9], exec, s[8:9]
	s_cbranch_execz .LBB0_79
	s_waitcnt lgkmcnt(0)
	buffer_inv sc1
	v_add_u32_e32 v1, 1, v1
	v_mul_lo_u32 v1, v1, v0
	v_mov_b32_e32 v0, 0
	s_add_u32 s22, s14, 0xff43500
	s_addc_u32 s23, s15, 0
	global_load_dword v0, v0, s[22:23] offset:-256 sc1
	s_waitcnt vmcnt(0)
	v_cmp_lt_u32_e32 vcc, v0, v1
	s_and_saveexec_b64 s[18:19], vcc
	s_cbranch_execz .LBB0_78
	s_add_u32 s20, s14, 0xff40200
	s_addc_u32 s21, s15, 0
	s_mov_b32 s26, 1
	s_mov_b64 s[30:31], 0
	v_mov_b32_e32 v0, 0
	s_branch .LBB0_69

.LBB0_71:
	global_load_dword v2, v0, s[22:23] offset:-256 sc1
	s_add_i32 s26, s26, 1
	s_mov_b64 s[40:41], -1
	s_waitcnt vmcnt(0)
	v_cmp_ge_u32_e32 vcc, v2, v1
	s_orn2_b64 s[36:37], vcc, exec
	s_branch .LBB0_68

; __device__ __forceinline__ unsigned xb_ld(unsigned* p)              { return __hip_atomic_load(p, __ATOMIC_RELAXED, __HIP_MEMORY_SCOPE_AGENT); }
; __device__ __forceinline__ unsigned xb_add(unsigned* p, unsigned v) { return __hip_atomic_fetch_add(p, v, __ATOMIC_RELAXED, __HIP_MEMORY_SCOPE_AGENT); }
; #define XB_SPIN(cond, bar) do { unsigned _sp = 0; while (cond) { __builtin_amdgcn_s_sleep(1); \
;     if ((++_sp & 255u) == 0u) { if (xb_ld(&(bar)[XB_TMO])) break; if (_sp > XB_SPIN_CAP) { atomicAdd(&(bar)[XB_TMO], 1u); break; } } } } while (0)
; __device__ __forceinline__ void xcd_barrier(const XcdBarrier& b, int wave_id) {
;     ...
;             const unsigned og = xb_add(&bar[XB_TOP], 1u);
;             const unsigned tg = og / nx;
;             if (og + 1u == (tg + 1u) * nx) xb_add(&bar[XB_TOPGEN], 1u);
;             else XB_SPIN(xb_ld(&bar[XB_TOPGEN]) == tg, bar);
.LBB0_82:
	s_or_b64 exec, exec, s[18:19]
	v_cvt_f32_u32_e32 v3, v0
	s_waitcnt vmcnt(0)
	v_readfirstlane_b32 s8, v2
	s_add_u32 s18, s14, 0xff43500
	s_addc_u32 s19, s15, 0
	v_rcp_iflag_f32_e32 v3, v3
	v_add_u32_e32 v1, s8, v1
	v_add_u32_e32 v4, 1, v1
	s_mov_b64 s[20:21], -1
	v_mul_f32_e32 v2, 0x4f7ffffe, v3
	v_cvt_u32_f32_e32 v2, v2
	v_sub_u32_e32 v3, 0, v0
	v_mul_lo_u32 v3, v3, v2
	v_mul_hi_u32 v3, v2, v3
	v_add_u32_e32 v2, v2, v3
	v_mul_hi_u32 v2, v1, v2
	v_mul_lo_u32 v3, v2, v0
	v_sub_u32_e32 v1, v1, v3
	v_add_u32_e32 v5, 1, v2
	v_cmp_ge_u32_e32 vcc, v1, v0
	v_sub_u32_e32 v3, v1, v0
	s_nop 0
	v_cndmask_b32_e32 v2, v2, v5, vcc
	v_cndmask_b32_e32 v1, v1, v3, vcc
	v_add_u32_e32 v3, 1, v2
	v_cmp_ge_u32_e32 vcc, v1, v0
	s_nop 1
	v_cndmask_b32_e32 v2, v2, v3, vcc
	v_mul_lo_u32 v1, v0, v2
	v_add_u32_e32 v0, v1, v0
	v_mov_b32_e32 v2, v0
	v_cmp_ne_u32_e32 vcc, v4, v0
	v_mov_b64_e32 v[0:1], s[18:19]
	s_and_saveexec_b64 s[8:9], vcc
	s_cbranch_execz .LBB0_94
	v_mov_b32_e32 v0, 0
	global_load_dword v1, v0, s[18:19] offset:-256 sc1
	s_mov_b64 s[30:31], 0
	s_waitcnt vmcnt(0)
	v_cmp_lt_u32_e32 vcc, v1, v2
	s_and_saveexec_b64 s[22:23], vcc
	s_cbranch_execz .LBB0_93
	s_add_u32 s20, s14, 0xff40200
	s_addc_u32 s21, s15, 0
	s_mov_b32 s26, 1
	s_branch .LBB0_86

.LBB0_88:
	global_load_dword v1, v0, s[18:19] offset:-256 sc1
	s_add_i32 s26, s26, 1
	s_mov_b64 s[36:37], -1
	s_waitcnt vmcnt(0)
	v_cmp_ge_u32_e32 vcc, v1, v2
	s_orn2_b64 s[42:43], vcc, exec
	s_branch .LBB0_85

; __device__ __forceinline__ unsigned xb_ld(unsigned* p)              { return __hip_atomic_load(p, __ATOMIC_RELAXED, __HIP_MEMORY_SCOPE_AGENT); }
; __device__ __forceinline__ unsigned xb_add(unsigned* p, unsigned v) { return __hip_atomic_fetch_add(p, v, __ATOMIC_RELAXED, __HIP_MEMORY_SCOPE_AGENT); }
; #define XB_SPIN(cond, bar) do { unsigned _sp = 0; while (cond) { __builtin_amdgcn_s_sleep(1); \
;     if ((++_sp & 255u) == 0u) { if (xb_ld(&(bar)[XB_TMO])) break; if (_sp > XB_SPIN_CAP) { atomicAdd(&(bar)[XB_TMO], 1u); break; } } } } while (0)
; __device__ __forceinline__ void xcd_barrier(const XcdBarrier& b, int wave_id) {
;     ...
;         const unsigned old = xb_add(&bar[XB_XSUB(b.x)], 1u);
;         const unsigned gen = old / nloc;
;         if (old + 1u == (gen + 1u) * nloc) {
;             __builtin_amdgcn_fence(__ATOMIC_RELEASE, "agent");
;             asm volatile("s_waitcnt vmcnt(0)" ::: "memory");
;             const unsigned og = xb_add(&bar[XB_TOP], 1u);
;             const unsigned tg = og / nx;
;             if (og + 1u == (tg + 1u) * nx) xb_add(&bar[XB_TOPGEN], 1u);
;             else XB_SPIN(xb_ld(&bar[XB_TOPGEN]) == tg, bar);
;             __builtin_amdgcn_fence(__ATOMIC_ACQUIRE, "agent");
;             xb_add(&bar[XB_XGEN(b.x)], 1u);
;             asm volatile("s_waitcnt vmcnt(0)" ::: "memory");
;         } else {
;             XB_SPIN(xb_ld(&bar[XB_XGEN(b.x)]) == gen, bar);
.LBB0_225:
	s_or_b64 exec, exec, s[10:11]
	v_cvt_f32_u32_e32 v4, v2
	s_waitcnt vmcnt(0)
	v_readfirstlane_b32 s8, v3
	v_sub_u32_e32 v3, 0, v2
	v_rcp_iflag_f32_e32 v4, v4
	v_add_u32_e32 v5, s8, v1
	v_mul_f32_e32 v4, 0x4f7ffffe, v4
	v_cvt_u32_f32_e32 v4, v4
	v_mul_lo_u32 v1, v3, v4
	v_mul_hi_u32 v1, v4, v1
	v_add_u32_e32 v1, v4, v1
	v_mul_hi_u32 v1, v5, v1
	v_mul_lo_u32 v3, v1, v2
	v_sub_u32_e32 v3, v5, v3
	v_add_u32_e32 v4, 1, v1
	v_cmp_ge_u32_e32 vcc, v3, v2
	s_nop 1
	v_cndmask_b32_e32 v1, v1, v4, vcc
	v_sub_u32_e32 v4, v3, v2
	v_cndmask_b32_e32 v3, v3, v4, vcc
	v_add_u32_e32 v4, 1, v1
	v_cmp_ge_u32_e32 vcc, v3, v2
	v_add_u32_e32 v3, 1, v5
	s_nop 0
	v_cndmask_b32_e32 v1, v1, v4, vcc
	v_mul_lo_u32 v4, v2, v1
	v_add_u32_e32 v2, v4, v2
	v_cmp_ne_u32_e32 vcc, v3, v2
	s_and_saveexec_b64 s[8:9], vcc
	s_xor_b64 s[8:9], exec, s[8:9]
	s_cbranch_execz .LBB0_239
	s_waitcnt lgkmcnt(0)
	buffer_inv sc1
	v_add_u32_e32 v1, 1, v1
	v_mul_lo_u32 v1, v1, v0
	v_mov_b32_e32 v0, 0
	s_add_u32 s22, s14, 0xff43500
	s_addc_u32 s23, s15, 0
	global_load_dword v0, v0, s[22:23] offset:-256 sc1
	s_waitcnt vmcnt(0)
	v_cmp_lt_u32_e32 vcc, v0, v1
	s_and_saveexec_b64 s[10:11], vcc
	s_cbranch_execz .LBB0_238
	s_add_u32 s20, s14, 0xff40200
	s_addc_u32 s21, s15, 0
	s_mov_b32 s26, 1
	s_mov_b64 s[44:45], 0
	v_mov_b32_e32 v0, 0
	s_branch .LBB0_229

.LBB0_231:
	global_load_dword v2, v0, s[22:23] offset:-256 sc1
	s_add_i32 s26, s26, 1
	s_mov_b64 s[50:51], -1
	s_waitcnt vmcnt(0)
	v_cmp_ge_u32_e32 vcc, v2, v1
	s_orn2_b64 s[48:49], vcc, exec
	s_branch .LBB0_228

; __device__ __forceinline__ unsigned xb_ld(unsigned* p)              { return __hip_atomic_load(p, __ATOMIC_RELAXED, __HIP_MEMORY_SCOPE_AGENT); }
; __device__ __forceinline__ unsigned xb_add(unsigned* p, unsigned v) { return __hip_atomic_fetch_add(p, v, __ATOMIC_RELAXED, __HIP_MEMORY_SCOPE_AGENT); }
; #define XB_SPIN(cond, bar) do { unsigned _sp = 0; while (cond) { __builtin_amdgcn_s_sleep(1); \
;     if ((++_sp & 255u) == 0u) { if (xb_ld(&(bar)[XB_TMO])) break; if (_sp > XB_SPIN_CAP) { atomicAdd(&(bar)[XB_TMO], 1u); break; } } } } while (0)
; __device__ __forceinline__ void xcd_barrier(const XcdBarrier& b, int wave_id) {
;     ...
;             const unsigned og = xb_add(&bar[XB_TOP], 1u);
;             const unsigned tg = og / nx;
;             if (og + 1u == (tg + 1u) * nx) xb_add(&bar[XB_TOPGEN], 1u);
;             else XB_SPIN(xb_ld(&bar[XB_TOPGEN]) == tg, bar);
.LBB0_242:
	s_or_b64 exec, exec, s[10:11]
	v_cvt_f32_u32_e32 v3, v0
	s_waitcnt vmcnt(0)
	v_readfirstlane_b32 s8, v2
	s_add_u32 s10, s14, 0xff43500
	s_addc_u32 s11, s15, 0
	v_rcp_iflag_f32_e32 v3, v3
	v_add_u32_e32 v1, s8, v1
	v_add_u32_e32 v4, 1, v1
	s_mov_b64 s[20:21], -1
	v_mul_f32_e32 v2, 0x4f7ffffe, v3
	v_cvt_u32_f32_e32 v2, v2
	v_sub_u32_e32 v3, 0, v0
	v_mul_lo_u32 v3, v3, v2
	v_mul_hi_u32 v3, v2, v3
	v_add_u32_e32 v2, v2, v3
	v_mul_hi_u32 v2, v1, v2
	v_mul_lo_u32 v3, v2, v0
	v_sub_u32_e32 v1, v1, v3
	v_add_u32_e32 v5, 1, v2
	v_cmp_ge_u32_e32 vcc, v1, v0
	v_sub_u32_e32 v3, v1, v0
	s_nop 0
	v_cndmask_b32_e32 v2, v2, v5, vcc
	v_cndmask_b32_e32 v1, v1, v3, vcc
	v_add_u32_e32 v3, 1, v2
	v_cmp_ge_u32_e32 vcc, v1, v0
	s_nop 1
	v_cndmask_b32_e32 v2, v2, v3, vcc
	v_mul_lo_u32 v1, v0, v2
	v_add_u32_e32 v0, v1, v0
	v_mov_b32_e32 v2, v0
	v_cmp_ne_u32_e32 vcc, v4, v0
	v_mov_b64_e32 v[0:1], s[10:11]
	s_and_saveexec_b64 s[8:9], vcc
	s_cbranch_execz .LBB0_254
	v_mov_b32_e32 v0, 0
	global_load_dword v1, v0, s[10:11] offset:-256 sc1
	s_mov_b64 s[44:45], 0
	s_waitcnt vmcnt(0)
	v_cmp_lt_u32_e32 vcc, v1, v2
	s_and_saveexec_b64 s[22:23], vcc
	s_cbranch_execz .LBB0_253
	s_add_u32 s20, s14, 0xff40200
	s_addc_u32 s21, s15, 0
	s_mov_b32 s26, 1
	s_branch .LBB0_246

.LBB0_248:
	global_load_dword v1, v0, s[10:11] offset:-256 sc1
	s_add_i32 s26, s26, 1
	s_mov_b64 s[48:49], -1
	s_waitcnt vmcnt(0)
	v_cmp_ge_u32_e32 vcc, v1, v2
	s_orn2_b64 s[52:53], vcc, exec
	s_branch .LBB0_245

; __device__ __forceinline__ unsigned xb_ld(unsigned* p)              { return __hip_atomic_load(p, __ATOMIC_RELAXED, __HIP_MEMORY_SCOPE_AGENT); }
; __device__ __forceinline__ unsigned xb_add(unsigned* p, unsigned v) { return __hip_atomic_fetch_add(p, v, __ATOMIC_RELAXED, __HIP_MEMORY_SCOPE_AGENT); }
; #define XB_SPIN(cond, bar) do { unsigned _sp = 0; while (cond) { __builtin_amdgcn_s_sleep(1); \
;     if ((++_sp & 255u) == 0u) { if (xb_ld(&(bar)[XB_TMO])) break; if (_sp > XB_SPIN_CAP) { atomicAdd(&(bar)[XB_TMO], 1u); break; } } } } while (0)
; __device__ __forceinline__ void xcd_barrier(const XcdBarrier& b, int wave_id) {
;     ...
;         const unsigned old = xb_add(&bar[XB_XSUB(b.x)], 1u);
;         const unsigned gen = old / nloc;
;         if (old + 1u == (gen + 1u) * nloc) {
;             __builtin_amdgcn_fence(__ATOMIC_RELEASE, "agent");
;             asm volatile("s_waitcnt vmcnt(0)" ::: "memory");
;             const unsigned og = xb_add(&bar[XB_TOP], 1u);
;             const unsigned tg = og / nx;
;             if (og + 1u == (tg + 1u) * nx) xb_add(&bar[XB_TOPGEN], 1u);
;             else XB_SPIN(xb_ld(&bar[XB_TOPGEN]) == tg, bar);
;             __builtin_amdgcn_fence(__ATOMIC_ACQUIRE, "agent");
;             xb_add(&bar[XB_XGEN(b.x)], 1u);
;             asm volatile("s_waitcnt vmcnt(0)" ::: "memory");
;         } else {
;             XB_SPIN(xb_ld(&bar[XB_XGEN(b.x)]) == gen, bar);
.LBB0_387:
	s_or_b64 exec, exec, s[22:23]
	v_cvt_f32_u32_e32 v4, v2
	s_waitcnt vmcnt(0)
	v_readfirstlane_b32 s6, v3
	v_sub_u32_e32 v3, 0, v2
	v_rcp_iflag_f32_e32 v4, v4
	v_add_u32_e32 v5, s6, v1
	v_mul_f32_e32 v4, 0x4f7ffffe, v4
	v_cvt_u32_f32_e32 v4, v4
	v_mul_lo_u32 v1, v3, v4
	v_mul_hi_u32 v1, v4, v1
	v_add_u32_e32 v1, v4, v1
	v_mul_hi_u32 v1, v5, v1
	v_mul_lo_u32 v3, v1, v2
	v_sub_u32_e32 v3, v5, v3
	v_add_u32_e32 v4, 1, v1
	v_cmp_ge_u32_e32 vcc, v3, v2
	s_nop 1
	v_cndmask_b32_e32 v1, v1, v4, vcc
	v_sub_u32_e32 v4, v3, v2
	v_cndmask_b32_e32 v3, v3, v4, vcc
	v_add_u32_e32 v4, 1, v1
	v_cmp_ge_u32_e32 vcc, v3, v2
	v_add_u32_e32 v3, 1, v5
	s_nop 0
	v_cndmask_b32_e32 v1, v1, v4, vcc
	v_mul_lo_u32 v4, v2, v1
	v_add_u32_e32 v2, v4, v2
	v_cmp_ne_u32_e32 vcc, v3, v2
	s_and_saveexec_b64 s[6:7], vcc
	s_xor_b64 s[20:21], exec, s[6:7]
	s_cbranch_execz .LBB0_401
	s_waitcnt lgkmcnt(0)
	buffer_inv sc1
	v_add_u32_e32 v1, 1, v1
	v_mul_lo_u32 v1, v1, v0
	v_mov_b32_e32 v0, 0
	s_add_u32 s44, s14, 0xff43500
	s_addc_u32 s45, s15, 0
	global_load_dword v0, v0, s[44:45] offset:-256 sc1
	s_waitcnt vmcnt(0)
	v_cmp_lt_u32_e32 vcc, v0, v1
	s_and_saveexec_b64 s[22:23], vcc
	s_cbranch_execz .LBB0_400
	s_add_u32 s42, s14, 0xff40200
	s_addc_u32 s43, s15, 0
	s_mov_b32 s6, 1
	s_mov_b64 s[46:47], 0
	v_mov_b32_e32 v0, 0
	s_branch .LBB0_391

.LBB0_393:
	global_load_dword v2, v0, s[44:45] offset:-256 sc1
	s_add_i32 s6, s6, 1
	s_mov_b64 s[52:53], -1
	s_waitcnt vmcnt(0)
	v_cmp_ge_u32_e32 vcc, v2, v1
	s_orn2_b64 s[50:51], vcc, exec
	s_branch .LBB0_390

; __device__ __forceinline__ unsigned xb_ld(unsigned* p)              { return __hip_atomic_load(p, __ATOMIC_RELAXED, __HIP_MEMORY_SCOPE_AGENT); }
; __device__ __forceinline__ unsigned xb_add(unsigned* p, unsigned v) { return __hip_atomic_fetch_add(p, v, __ATOMIC_RELAXED, __HIP_MEMORY_SCOPE_AGENT); }
; #define XB_SPIN(cond, bar) do { unsigned _sp = 0; while (cond) { __builtin_amdgcn_s_sleep(1); \
;     if ((++_sp & 255u) == 0u) { if (xb_ld(&(bar)[XB_TMO])) break; if (_sp > XB_SPIN_CAP) { atomicAdd(&(bar)[XB_TMO], 1u); break; } } } } while (0)
; __device__ __forceinline__ void xcd_barrier(const XcdBarrier& b, int wave_id) {
;     ...
;             const unsigned og = xb_add(&bar[XB_TOP], 1u);
;             const unsigned tg = og / nx;
;             if (og + 1u == (tg + 1u) * nx) xb_add(&bar[XB_TOPGEN], 1u);
;             else XB_SPIN(xb_ld(&bar[XB_TOPGEN]) == tg, bar);
.LBB0_404:
	s_or_b64 exec, exec, s[22:23]
	v_cvt_f32_u32_e32 v3, v0
	s_waitcnt vmcnt(0)
	v_readfirstlane_b32 s6, v2
	s_add_u32 s22, s14, 0xff43500
	s_addc_u32 s23, s15, 0
	v_rcp_iflag_f32_e32 v3, v3
	v_add_u32_e32 v1, s6, v1
	v_add_u32_e32 v4, 1, v1
	s_mov_b64 s[42:43], -1
	v_mul_f32_e32 v2, 0x4f7ffffe, v3
	v_cvt_u32_f32_e32 v2, v2
	v_sub_u32_e32 v3, 0, v0
	v_mul_lo_u32 v3, v3, v2
	v_mul_hi_u32 v3, v2, v3
	v_add_u32_e32 v2, v2, v3
	v_mul_hi_u32 v2, v1, v2
	v_mul_lo_u32 v3, v2, v0
	v_sub_u32_e32 v1, v1, v3
	v_add_u32_e32 v5, 1, v2
	v_cmp_ge_u32_e32 vcc, v1, v0
	v_sub_u32_e32 v3, v1, v0
	s_nop 0
	v_cndmask_b32_e32 v2, v2, v5, vcc
	v_cndmask_b32_e32 v1, v1, v3, vcc
	v_add_u32_e32 v3, 1, v2
	v_cmp_ge_u32_e32 vcc, v1, v0
	s_nop 1
	v_cndmask_b32_e32 v2, v2, v3, vcc
	v_mul_lo_u32 v1, v0, v2
	v_add_u32_e32 v0, v1, v0
	v_mov_b32_e32 v2, v0
	v_cmp_ne_u32_e32 vcc, v4, v0
	v_mov_b64_e32 v[0:1], s[22:23]
	s_and_saveexec_b64 s[20:21], vcc
	s_cbranch_execz .LBB0_416
	v_mov_b32_e32 v0, 0
	global_load_dword v1, v0, s[22:23] offset:-256 sc1
	s_mov_b64 s[46:47], 0
	s_waitcnt vmcnt(0)
	v_cmp_lt_u32_e32 vcc, v1, v2
	s_and_saveexec_b64 s[44:45], vcc
	s_cbranch_execz .LBB0_415
	s_add_u32 s42, s14, 0xff40200
	s_addc_u32 s43, s15, 0
	s_mov_b32 s6, 1
	s_branch .LBB0_408

.LBB0_410:
	global_load_dword v1, v0, s[22:23] offset:-256 sc1
	s_add_i32 s6, s6, 1
	s_mov_b64 s[50:51], -1
	s_waitcnt vmcnt(0)
	v_cmp_ge_u32_e32 vcc, v1, v2
	s_orn2_b64 s[54:55], vcc, exec
	s_branch .LBB0_407

; __device__ __forceinline__ unsigned xb_ld(unsigned* p)              { return __hip_atomic_load(p, __ATOMIC_RELAXED, __HIP_MEMORY_SCOPE_AGENT); }
; __device__ __forceinline__ unsigned xb_add(unsigned* p, unsigned v) { return __hip_atomic_fetch_add(p, v, __ATOMIC_RELAXED, __HIP_MEMORY_SCOPE_AGENT); }
; #define XB_SPIN(cond, bar) do { unsigned _sp = 0; while (cond) { __builtin_amdgcn_s_sleep(1); \
;     if ((++_sp & 255u) == 0u) { if (xb_ld(&(bar)[XB_TMO])) break; if (_sp > XB_SPIN_CAP) { atomicAdd(&(bar)[XB_TMO], 1u); break; } } } } while (0)
; __device__ __forceinline__ void xcd_barrier(const XcdBarrier& b, int wave_id) {
;     ...
;         const unsigned old = xb_add(&bar[XB_XSUB(b.x)], 1u);
;         const unsigned gen = old / nloc;
;         if (old + 1u == (gen + 1u) * nloc) {
;             __builtin_amdgcn_fence(__ATOMIC_RELEASE, "agent");
;             asm volatile("s_waitcnt vmcnt(0)" ::: "memory");
;             const unsigned og = xb_add(&bar[XB_TOP], 1u);
;             const unsigned tg = og / nx;
;             if (og + 1u == (tg + 1u) * nx) xb_add(&bar[XB_TOPGEN], 1u);
;             else XB_SPIN(xb_ld(&bar[XB_TOPGEN]) == tg, bar);
;             __builtin_amdgcn_fence(__ATOMIC_ACQUIRE, "agent");
;             xb_add(&bar[XB_XGEN(b.x)], 1u);
;             asm volatile("s_waitcnt vmcnt(0)" ::: "memory");
;         } else {
;             XB_SPIN(xb_ld(&bar[XB_XGEN(b.x)]) == gen, bar);
.LBB0_470:
	s_or_b64 exec, exec, s[22:23]
	v_cvt_f32_u32_e32 v4, v2
	s_waitcnt vmcnt(0)
	v_readfirstlane_b32 s6, v3
	v_sub_u32_e32 v3, 0, v2
	v_rcp_iflag_f32_e32 v4, v4
	v_add_u32_e32 v5, s6, v1
	v_mul_f32_e32 v4, 0x4f7ffffe, v4
	v_cvt_u32_f32_e32 v4, v4
	v_mul_lo_u32 v1, v3, v4
	v_mul_hi_u32 v1, v4, v1
	v_add_u32_e32 v1, v4, v1
	v_mul_hi_u32 v1, v5, v1
	v_mul_lo_u32 v3, v1, v2
	v_sub_u32_e32 v3, v5, v3
	v_add_u32_e32 v4, 1, v1
	v_cmp_ge_u32_e32 vcc, v3, v2
	s_nop 1
	v_cndmask_b32_e32 v1, v1, v4, vcc
	v_sub_u32_e32 v4, v3, v2
	v_cndmask_b32_e32 v3, v3, v4, vcc
	v_add_u32_e32 v4, 1, v1
	v_cmp_ge_u32_e32 vcc, v3, v2
	v_add_u32_e32 v3, 1, v5
	s_nop 0
	v_cndmask_b32_e32 v1, v1, v4, vcc
	v_mul_lo_u32 v4, v2, v1
	v_add_u32_e32 v2, v4, v2
	v_cmp_ne_u32_e32 vcc, v3, v2
	s_and_saveexec_b64 s[6:7], vcc
	s_xor_b64 s[10:11], exec, s[6:7]
	s_cbranch_execz .LBB0_484
	s_waitcnt lgkmcnt(0)
	buffer_inv sc1
	v_add_u32_e32 v1, 1, v1
	v_mul_lo_u32 v1, v1, v0
	v_mov_b32_e32 v0, 0
	s_add_u32 s40, s14, 0xff43500
	s_addc_u32 s41, s15, 0
	global_load_dword v0, v0, s[40:41] offset:-256 sc1
	s_waitcnt vmcnt(0)
	v_cmp_lt_u32_e32 vcc, v0, v1
	s_and_saveexec_b64 s[22:23], vcc
	s_cbranch_execz .LBB0_483
	s_add_u32 s38, s14, 0xff40200
	s_addc_u32 s39, s15, 0
	s_mov_b32 s6, 1
	s_mov_b64 s[42:43], 0
	v_mov_b32_e32 v0, 0
	s_branch .LBB0_474

.LBB0_476:
	global_load_dword v2, v0, s[40:41] offset:-256 sc1
	s_add_i32 s6, s6, 1
	s_mov_b64 s[48:49], -1
	s_waitcnt vmcnt(0)
	v_cmp_ge_u32_e32 vcc, v2, v1
	s_orn2_b64 s[46:47], vcc, exec
	s_branch .LBB0_473

; __device__ __forceinline__ unsigned xb_ld(unsigned* p)              { return __hip_atomic_load(p, __ATOMIC_RELAXED, __HIP_MEMORY_SCOPE_AGENT); }
; __device__ __forceinline__ unsigned xb_add(unsigned* p, unsigned v) { return __hip_atomic_fetch_add(p, v, __ATOMIC_RELAXED, __HIP_MEMORY_SCOPE_AGENT); }
; #define XB_SPIN(cond, bar) do { unsigned _sp = 0; while (cond) { __builtin_amdgcn_s_sleep(1); \
;     if ((++_sp & 255u) == 0u) { if (xb_ld(&(bar)[XB_TMO])) break; if (_sp > XB_SPIN_CAP) { atomicAdd(&(bar)[XB_TMO], 1u); break; } } } } while (0)
; __device__ __forceinline__ void xcd_barrier(const XcdBarrier& b, int wave_id) {
;     ...
;             const unsigned og = xb_add(&bar[XB_TOP], 1u);
;             const unsigned tg = og / nx;
;             if (og + 1u == (tg + 1u) * nx) xb_add(&bar[XB_TOPGEN], 1u);
;             else XB_SPIN(xb_ld(&bar[XB_TOPGEN]) == tg, bar);
.LBB0_487:
	s_or_b64 exec, exec, s[22:23]
	v_cvt_f32_u32_e32 v3, v0
	s_waitcnt vmcnt(0)
	v_readfirstlane_b32 s6, v2
	s_add_u32 s22, s14, 0xff43500
	s_addc_u32 s23, s15, 0
	v_rcp_iflag_f32_e32 v3, v3
	v_add_u32_e32 v1, s6, v1
	v_add_u32_e32 v4, 1, v1
	s_mov_b64 s[38:39], -1
	v_mul_f32_e32 v2, 0x4f7ffffe, v3
	v_cvt_u32_f32_e32 v2, v2
	v_sub_u32_e32 v3, 0, v0
	v_mul_lo_u32 v3, v3, v2
	v_mul_hi_u32 v3, v2, v3
	v_add_u32_e32 v2, v2, v3
	v_mul_hi_u32 v2, v1, v2
	v_mul_lo_u32 v3, v2, v0
	v_sub_u32_e32 v1, v1, v3
	v_add_u32_e32 v5, 1, v2
	v_cmp_ge_u32_e32 vcc, v1, v0
	v_sub_u32_e32 v3, v1, v0
	s_nop 0
	v_cndmask_b32_e32 v2, v2, v5, vcc
	v_cndmask_b32_e32 v1, v1, v3, vcc
	v_add_u32_e32 v3, 1, v2
	v_cmp_ge_u32_e32 vcc, v1, v0
	s_nop 1
	v_cndmask_b32_e32 v2, v2, v3, vcc
	v_mul_lo_u32 v1, v0, v2
	v_add_u32_e32 v0, v1, v0
	v_mov_b32_e32 v2, v0
	v_cmp_ne_u32_e32 vcc, v4, v0
	v_mov_b64_e32 v[0:1], s[22:23]
	s_and_saveexec_b64 s[10:11], vcc
	s_cbranch_execz .LBB0_499
	v_mov_b32_e32 v0, 0
	global_load_dword v1, v0, s[22:23] offset:-256 sc1
	s_mov_b64 s[42:43], 0
	s_waitcnt vmcnt(0)
	v_cmp_lt_u32_e32 vcc, v1, v2
	s_and_saveexec_b64 s[40:41], vcc
	s_cbranch_execz .LBB0_498
	s_add_u32 s38, s14, 0xff40200
	s_addc_u32 s39, s15, 0
	s_mov_b32 s6, 1
	s_branch .LBB0_491

.LBB0_493:
	global_load_dword v1, v0, s[22:23] offset:-256 sc1
	s_add_i32 s6, s6, 1
	s_mov_b64 s[46:47], -1
	s_waitcnt vmcnt(0)
	v_cmp_ge_u32_e32 vcc, v1, v2
	s_orn2_b64 s[50:51], vcc, exec
	s_branch .LBB0_490

; __device__ __forceinline__ unsigned xb_ld(unsigned* p)              { return __hip_atomic_load(p, __ATOMIC_RELAXED, __HIP_MEMORY_SCOPE_AGENT); }
; __device__ __forceinline__ unsigned xb_add(unsigned* p, unsigned v) { return __hip_atomic_fetch_add(p, v, __ATOMIC_RELAXED, __HIP_MEMORY_SCOPE_AGENT); }
; #define XB_SPIN(cond, bar) do { unsigned _sp = 0; while (cond) { __builtin_amdgcn_s_sleep(1); \
;     if ((++_sp & 255u) == 0u) { if (xb_ld(&(bar)[XB_TMO])) break; if (_sp > XB_SPIN_CAP) { atomicAdd(&(bar)[XB_TMO], 1u); break; } } } } while (0)
; __device__ __forceinline__ void xcd_barrier(const XcdBarrier& b, int wave_id) {
;     ...
;         const unsigned old = xb_add(&bar[XB_XSUB(b.x)], 1u);
;         const unsigned gen = old / nloc;
;         if (old + 1u == (gen + 1u) * nloc) {
;             __builtin_amdgcn_fence(__ATOMIC_RELEASE, "agent");
;             asm volatile("s_waitcnt vmcnt(0)" ::: "memory");
;             const unsigned og = xb_add(&bar[XB_TOP], 1u);
;             const unsigned tg = og / nx;
;             if (og + 1u == (tg + 1u) * nx) xb_add(&bar[XB_TOPGEN], 1u);
;             else XB_SPIN(xb_ld(&bar[XB_TOPGEN]) == tg, bar);
;             __builtin_amdgcn_fence(__ATOMIC_ACQUIRE, "agent");
;             xb_add(&bar[XB_XGEN(b.x)], 1u);
;             asm volatile("s_waitcnt vmcnt(0)" ::: "memory");
;         } else {
;             XB_SPIN(xb_ld(&bar[XB_XGEN(b.x)]) == gen, bar);
.LBB0_578:
	s_or_b64 exec, exec, s[22:23]
	v_cvt_f32_u32_e32 v4, v2
	s_waitcnt vmcnt(0)
	v_readfirstlane_b32 s8, v3
	v_sub_u32_e32 v3, 0, v2
	v_rcp_iflag_f32_e32 v4, v4
	v_add_u32_e32 v5, s8, v1
	v_mul_f32_e32 v4, 0x4f7ffffe, v4
	v_cvt_u32_f32_e32 v4, v4
	v_mul_lo_u32 v1, v3, v4
	v_mul_hi_u32 v1, v4, v1
	v_add_u32_e32 v1, v4, v1
	v_mul_hi_u32 v1, v5, v1
	v_mul_lo_u32 v3, v1, v2
	v_sub_u32_e32 v3, v5, v3
	v_add_u32_e32 v4, 1, v1
	v_cmp_ge_u32_e32 vcc, v3, v2
	s_nop 1
	v_cndmask_b32_e32 v1, v1, v4, vcc
	v_sub_u32_e32 v4, v3, v2
	v_cndmask_b32_e32 v3, v3, v4, vcc
	v_add_u32_e32 v4, 1, v1
	v_cmp_ge_u32_e32 vcc, v3, v2
	v_add_u32_e32 v3, 1, v5
	s_nop 0
	v_cndmask_b32_e32 v1, v1, v4, vcc
	v_mul_lo_u32 v4, v2, v1
	v_add_u32_e32 v2, v4, v2
	v_cmp_ne_u32_e32 vcc, v3, v2
	s_and_saveexec_b64 s[8:9], vcc
	s_xor_b64 s[8:9], exec, s[8:9]
	s_cbranch_execz .LBB0_592
	s_waitcnt lgkmcnt(0)
	buffer_inv sc1
	v_add_u32_e32 v1, 1, v1
	v_mul_lo_u32 v1, v1, v0
	v_mov_b32_e32 v0, 0
	s_add_u32 s40, s14, 0xff43500
	s_addc_u32 s41, s15, 0
	global_load_dword v0, v0, s[40:41] offset:-256 sc1
	s_waitcnt vmcnt(0)
	v_cmp_lt_u32_e32 vcc, v0, v1
	s_and_saveexec_b64 s[22:23], vcc
	s_cbranch_execz .LBB0_591
	s_add_u32 s38, s14, 0xff40200
	s_addc_u32 s39, s15, 0
	s_mov_b32 s26, 1
	s_mov_b64 s[42:43], 0
	v_mov_b32_e32 v0, 0
	s_branch .LBB0_582

.LBB0_584:
	global_load_dword v2, v0, s[40:41] offset:-256 sc1
	s_add_i32 s26, s26, 1
	s_mov_b64 s[48:49], -1
	s_waitcnt vmcnt(0)
	v_cmp_ge_u32_e32 vcc, v2, v1
	s_orn2_b64 s[46:47], vcc, exec
	s_branch .LBB0_581

; __device__ __forceinline__ unsigned xb_ld(unsigned* p)              { return __hip_atomic_load(p, __ATOMIC_RELAXED, __HIP_MEMORY_SCOPE_AGENT); }
; __device__ __forceinline__ unsigned xb_add(unsigned* p, unsigned v) { return __hip_atomic_fetch_add(p, v, __ATOMIC_RELAXED, __HIP_MEMORY_SCOPE_AGENT); }
; #define XB_SPIN(cond, bar) do { unsigned _sp = 0; while (cond) { __builtin_amdgcn_s_sleep(1); \
;     if ((++_sp & 255u) == 0u) { if (xb_ld(&(bar)[XB_TMO])) break; if (_sp > XB_SPIN_CAP) { atomicAdd(&(bar)[XB_TMO], 1u); break; } } } } while (0)
; __device__ __forceinline__ void xcd_barrier(const XcdBarrier& b, int wave_id) {
;     ...
;             const unsigned og = xb_add(&bar[XB_TOP], 1u);
;             const unsigned tg = og / nx;
;             if (og + 1u == (tg + 1u) * nx) xb_add(&bar[XB_TOPGEN], 1u);
;             else XB_SPIN(xb_ld(&bar[XB_TOPGEN]) == tg, bar);
.LBB0_595:
	s_or_b64 exec, exec, s[22:23]
	v_cvt_f32_u32_e32 v3, v0
	s_waitcnt vmcnt(0)
	v_readfirstlane_b32 s8, v2
	s_add_u32 s22, s14, 0xff43500
	s_addc_u32 s23, s15, 0
	v_rcp_iflag_f32_e32 v3, v3
	v_add_u32_e32 v1, s8, v1
	v_add_u32_e32 v4, 1, v1
	s_mov_b64 s[38:39], -1
	v_mul_f32_e32 v2, 0x4f7ffffe, v3
	v_cvt_u32_f32_e32 v2, v2
	v_sub_u32_e32 v3, 0, v0
	v_mul_lo_u32 v3, v3, v2
	v_mul_hi_u32 v3, v2, v3
	v_add_u32_e32 v2, v2, v3
	v_mul_hi_u32 v2, v1, v2
	v_mul_lo_u32 v3, v2, v0
	v_sub_u32_e32 v1, v1, v3
	v_add_u32_e32 v5, 1, v2
	v_cmp_ge_u32_e32 vcc, v1, v0
	v_sub_u32_e32 v3, v1, v0
	s_nop 0
	v_cndmask_b32_e32 v2, v2, v5, vcc
	v_cndmask_b32_e32 v1, v1, v3, vcc
	v_add_u32_e32 v3, 1, v2
	v_cmp_ge_u32_e32 vcc, v1, v0
	s_nop 1
	v_cndmask_b32_e32 v2, v2, v3, vcc
	v_mul_lo_u32 v1, v0, v2
	v_add_u32_e32 v0, v1, v0
	v_mov_b32_e32 v2, v0
	v_cmp_ne_u32_e32 vcc, v4, v0
	v_mov_b64_e32 v[0:1], s[22:23]
	s_and_saveexec_b64 s[8:9], vcc
	s_cbranch_execz .LBB0_607
	v_mov_b32_e32 v0, 0
	global_load_dword v1, v0, s[22:23] offset:-256 sc1
	s_mov_b64 s[42:43], 0
	s_waitcnt vmcnt(0)
	v_cmp_lt_u32_e32 vcc, v1, v2
	s_and_saveexec_b64 s[40:41], vcc
	s_cbranch_execz .LBB0_606
	s_add_u32 s38, s14, 0xff40200
	s_addc_u32 s39, s15, 0
	s_mov_b32 s26, 1
	s_branch .LBB0_599

.LBB0_601:
	global_load_dword v1, v0, s[22:23] offset:-256 sc1
	s_add_i32 s26, s26, 1
	s_mov_b64 s[46:47], -1
	s_waitcnt vmcnt(0)
	v_cmp_ge_u32_e32 vcc, v1, v2
	s_orn2_b64 s[50:51], vcc, exec
	s_branch .LBB0_598

; __device__ __forceinline__ unsigned xb_ld(unsigned* p)              { return __hip_atomic_load(p, __ATOMIC_RELAXED, __HIP_MEMORY_SCOPE_AGENT); }
; __device__ __forceinline__ unsigned xb_add(unsigned* p, unsigned v) { return __hip_atomic_fetch_add(p, v, __ATOMIC_RELAXED, __HIP_MEMORY_SCOPE_AGENT); }
; #define XB_SPIN(cond, bar) do { unsigned _sp = 0; while (cond) { __builtin_amdgcn_s_sleep(1); \
;     if ((++_sp & 255u) == 0u) { if (xb_ld(&(bar)[XB_TMO])) break; if (_sp > XB_SPIN_CAP) { atomicAdd(&(bar)[XB_TMO], 1u); break; } } } } while (0)
; __device__ __forceinline__ void xcd_barrier(const XcdBarrier& b, int wave_id) {
;     ...
;         const unsigned old = xb_add(&bar[XB_XSUB(b.x)], 1u);
;         const unsigned gen = old / nloc;
;         if (old + 1u == (gen + 1u) * nloc) {
;             __builtin_amdgcn_fence(__ATOMIC_RELEASE, "agent");
;             asm volatile("s_waitcnt vmcnt(0)" ::: "memory");
;             const unsigned og = xb_add(&bar[XB_TOP], 1u);
;             const unsigned tg = og / nx;
;             if (og + 1u == (tg + 1u) * nx) xb_add(&bar[XB_TOPGEN], 1u);
;             else XB_SPIN(xb_ld(&bar[XB_TOPGEN]) == tg, bar);
;             __builtin_amdgcn_fence(__ATOMIC_ACQUIRE, "agent");
;             xb_add(&bar[XB_XGEN(b.x)], 1u);
;             asm volatile("s_waitcnt vmcnt(0)" ::: "memory");
;         } else {
;             XB_SPIN(xb_ld(&bar[XB_XGEN(b.x)]) == gen, bar);
.LBB0_674:
	s_or_b64 exec, exec, s[16:17]
	v_cvt_f32_u32_e32 v4, v2
	s_waitcnt vmcnt(0)
	v_readfirstlane_b32 s8, v3
	v_sub_u32_e32 v3, 0, v2
	v_rcp_iflag_f32_e32 v4, v4
	v_add_u32_e32 v5, s8, v1
	v_mul_f32_e32 v4, 0x4f7ffffe, v4
	v_cvt_u32_f32_e32 v4, v4
	v_mul_lo_u32 v1, v3, v4
	v_mul_hi_u32 v1, v4, v1
	v_add_u32_e32 v1, v4, v1
	v_mul_hi_u32 v1, v5, v1
	v_mul_lo_u32 v3, v1, v2
	v_sub_u32_e32 v3, v5, v3
	v_add_u32_e32 v4, 1, v1
	v_cmp_ge_u32_e32 vcc, v3, v2
	s_nop 1
	v_cndmask_b32_e32 v1, v1, v4, vcc
	v_sub_u32_e32 v4, v3, v2
	v_cndmask_b32_e32 v3, v3, v4, vcc
	v_add_u32_e32 v4, 1, v1
	v_cmp_ge_u32_e32 vcc, v3, v2
	v_add_u32_e32 v3, 1, v5
	s_nop 0
	v_cndmask_b32_e32 v1, v1, v4, vcc
	v_mul_lo_u32 v4, v2, v1
	v_add_u32_e32 v2, v4, v2
	v_cmp_ne_u32_e32 vcc, v3, v2
	s_and_saveexec_b64 s[8:9], vcc
	s_xor_b64 s[8:9], exec, s[8:9]
	s_cbranch_execz .LBB0_688
	s_waitcnt lgkmcnt(0)
	buffer_inv sc1
	v_add_u32_e32 v1, 1, v1
	v_mul_lo_u32 v1, v1, v0
	v_mov_b32_e32 v0, 0
	s_add_u32 s22, s14, 0xff43500
	s_addc_u32 s23, s15, 0
	global_load_dword v0, v0, s[22:23] offset:-256 sc1
	s_waitcnt vmcnt(0)
	v_cmp_lt_u32_e32 vcc, v0, v1
	s_and_saveexec_b64 s[16:17], vcc
	s_cbranch_execz .LBB0_687
	s_add_u32 s20, s14, 0xff40200
	s_addc_u32 s21, s15, 0
	s_mov_b32 s26, 1
	s_mov_b64 s[36:37], 0
	v_mov_b32_e32 v0, 0
	s_branch .LBB0_678

.LBB0_680:
	global_load_dword v2, v0, s[22:23] offset:-256 sc1
	s_add_i32 s26, s26, 1
	s_mov_b64 s[42:43], -1
	s_waitcnt vmcnt(0)
	v_cmp_ge_u32_e32 vcc, v2, v1
	s_orn2_b64 s[40:41], vcc, exec
	s_branch .LBB0_677

; __device__ __forceinline__ unsigned xb_ld(unsigned* p)              { return __hip_atomic_load(p, __ATOMIC_RELAXED, __HIP_MEMORY_SCOPE_AGENT); }
; __device__ __forceinline__ unsigned xb_add(unsigned* p, unsigned v) { return __hip_atomic_fetch_add(p, v, __ATOMIC_RELAXED, __HIP_MEMORY_SCOPE_AGENT); }
; #define XB_SPIN(cond, bar) do { unsigned _sp = 0; while (cond) { __builtin_amdgcn_s_sleep(1); \
;     if ((++_sp & 255u) == 0u) { if (xb_ld(&(bar)[XB_TMO])) break; if (_sp > XB_SPIN_CAP) { atomicAdd(&(bar)[XB_TMO], 1u); break; } } } } while (0)
; __device__ __forceinline__ void xcd_barrier(const XcdBarrier& b, int wave_id) {
;     ...
;             const unsigned og = xb_add(&bar[XB_TOP], 1u);
;             const unsigned tg = og / nx;
;             if (og + 1u == (tg + 1u) * nx) xb_add(&bar[XB_TOPGEN], 1u);
;             else XB_SPIN(xb_ld(&bar[XB_TOPGEN]) == tg, bar);
.LBB0_691:
	s_or_b64 exec, exec, s[16:17]
	v_cvt_f32_u32_e32 v3, v0
	s_waitcnt vmcnt(0)
	v_readfirstlane_b32 s8, v2
	s_add_u32 s16, s14, 0xff43500
	s_addc_u32 s17, s15, 0
	v_rcp_iflag_f32_e32 v3, v3
	v_add_u32_e32 v1, s8, v1
	v_add_u32_e32 v4, 1, v1
	s_mov_b64 s[20:21], -1
	v_mul_f32_e32 v2, 0x4f7ffffe, v3
	v_cvt_u32_f32_e32 v2, v2
	v_sub_u32_e32 v3, 0, v0
	v_mul_lo_u32 v3, v3, v2
	v_mul_hi_u32 v3, v2, v3
	v_add_u32_e32 v2, v2, v3
	v_mul_hi_u32 v2, v1, v2
	v_mul_lo_u32 v3, v2, v0
	v_sub_u32_e32 v1, v1, v3
	v_add_u32_e32 v5, 1, v2
	v_cmp_ge_u32_e32 vcc, v1, v0
	v_sub_u32_e32 v3, v1, v0
	s_nop 0
	v_cndmask_b32_e32 v2, v2, v5, vcc
	v_cndmask_b32_e32 v1, v1, v3, vcc
	v_add_u32_e32 v3, 1, v2
	v_cmp_ge_u32_e32 vcc, v1, v0
	s_nop 1
	v_cndmask_b32_e32 v2, v2, v3, vcc
	v_mul_lo_u32 v1, v0, v2
	v_add_u32_e32 v0, v1, v0
	v_mov_b32_e32 v2, v0
	v_cmp_ne_u32_e32 vcc, v4, v0
	v_mov_b64_e32 v[0:1], s[16:17]
	s_and_saveexec_b64 s[8:9], vcc
	s_cbranch_execz .LBB0_703
	v_mov_b32_e32 v0, 0
	global_load_dword v1, v0, s[16:17] offset:-256 sc1
	s_mov_b64 s[36:37], 0
	s_waitcnt vmcnt(0)
	v_cmp_lt_u32_e32 vcc, v1, v2
	s_and_saveexec_b64 s[22:23], vcc
	s_cbranch_execz .LBB0_702
	s_add_u32 s20, s14, 0xff40200
	s_addc_u32 s21, s15, 0
	s_mov_b32 s26, 1
	s_branch .LBB0_695

.LBB0_697:
	global_load_dword v1, v0, s[16:17] offset:-256 sc1
	s_add_i32 s26, s26, 1
	s_mov_b64 s[40:41], -1
	s_waitcnt vmcnt(0)
	v_cmp_ge_u32_e32 vcc, v1, v2
	s_orn2_b64 s[44:45], vcc, exec
	s_branch .LBB0_694

; __device__ __forceinline__ unsigned xb_ld(unsigned* p)              { return __hip_atomic_load(p, __ATOMIC_RELAXED, __HIP_MEMORY_SCOPE_AGENT); }
; __device__ __forceinline__ unsigned xb_add(unsigned* p, unsigned v) { return __hip_atomic_fetch_add(p, v, __ATOMIC_RELAXED, __HIP_MEMORY_SCOPE_AGENT); }
; #define XB_SPIN(cond, bar) do { unsigned _sp = 0; while (cond) { __builtin_amdgcn_s_sleep(1); \
;     if ((++_sp & 255u) == 0u) { if (xb_ld(&(bar)[XB_TMO])) break; if (_sp > XB_SPIN_CAP) { atomicAdd(&(bar)[XB_TMO], 1u); break; } } } } while (0)
; __device__ __forceinline__ void xcd_barrier(const XcdBarrier& b, int wave_id) {
;     ...
;         const unsigned old = xb_add(&bar[XB_XSUB(b.x)], 1u);
;         const unsigned gen = old / nloc;
;         if (old + 1u == (gen + 1u) * nloc) {
;             __builtin_amdgcn_fence(__ATOMIC_RELEASE, "agent");
;             asm volatile("s_waitcnt vmcnt(0)" ::: "memory");
;             const unsigned og = xb_add(&bar[XB_TOP], 1u);
;             const unsigned tg = og / nx;
;             if (og + 1u == (tg + 1u) * nx) xb_add(&bar[XB_TOPGEN], 1u);
;             else XB_SPIN(xb_ld(&bar[XB_TOPGEN]) == tg, bar);
;             __builtin_amdgcn_fence(__ATOMIC_ACQUIRE, "agent");
;             xb_add(&bar[XB_XGEN(b.x)], 1u);
;             asm volatile("s_waitcnt vmcnt(0)" ::: "memory");
;         } else {
;             XB_SPIN(xb_ld(&bar[XB_XGEN(b.x)]) == gen, bar);
.LBB0_750:
	s_or_b64 exec, exec, s[18:19]
	v_cvt_f32_u32_e32 v4, v2
	s_waitcnt vmcnt(0)
	v_readfirstlane_b32 s3, v3
	v_sub_u32_e32 v3, 0, v2
	v_rcp_iflag_f32_e32 v4, v4
	v_add_u32_e32 v5, s3, v1
	v_mul_f32_e32 v4, 0x4f7ffffe, v4
	v_cvt_u32_f32_e32 v4, v4
	v_mul_lo_u32 v1, v3, v4
	v_mul_hi_u32 v1, v4, v1
	v_add_u32_e32 v1, v4, v1
	v_mul_hi_u32 v1, v5, v1
	v_mul_lo_u32 v3, v1, v2
	v_sub_u32_e32 v3, v5, v3
	v_add_u32_e32 v4, 1, v1
	v_cmp_ge_u32_e32 vcc, v3, v2
	s_nop 1
	v_cndmask_b32_e32 v1, v1, v4, vcc
	v_sub_u32_e32 v4, v3, v2
	v_cndmask_b32_e32 v3, v3, v4, vcc
	v_add_u32_e32 v4, 1, v1
	v_cmp_ge_u32_e32 vcc, v3, v2
	v_add_u32_e32 v3, 1, v5
	s_nop 0
	v_cndmask_b32_e32 v1, v1, v4, vcc
	v_mul_lo_u32 v4, v2, v1
	v_add_u32_e32 v2, v4, v2
	v_cmp_ne_u32_e32 vcc, v3, v2
	s_and_saveexec_b64 s[16:17], vcc
	s_xor_b64 s[16:17], exec, s[16:17]
	s_cbranch_execz .LBB0_764
	s_waitcnt lgkmcnt(0)
	buffer_inv sc1
	v_add_u32_e32 v1, 1, v1
	v_mul_lo_u32 v1, v1, v0
	v_mov_b32_e32 v0, 0
	s_add_u32 s22, s14, 0xff43500
	s_addc_u32 s23, s15, 0
	global_load_dword v0, v0, s[22:23] offset:-256 sc1
	s_waitcnt vmcnt(0)
	v_cmp_lt_u32_e32 vcc, v0, v1
	s_and_saveexec_b64 s[18:19], vcc
	s_cbranch_execz .LBB0_763
	s_add_u32 s20, s14, 0xff40200
	s_addc_u32 s21, s15, 0
	s_mov_b32 s3, 1
	s_mov_b64 s[26:27], 0
	v_mov_b32_e32 v0, 0
	s_branch .LBB0_754

.LBB0_756:
	global_load_dword v2, v0, s[22:23] offset:-256 sc1
	s_add_i32 s3, s3, 1
	s_mov_b64 s[34:35], -1
	s_waitcnt vmcnt(0)
	v_cmp_ge_u32_e32 vcc, v2, v1
	s_orn2_b64 s[30:31], vcc, exec
	s_branch .LBB0_753

; __device__ __forceinline__ unsigned xb_ld(unsigned* p)              { return __hip_atomic_load(p, __ATOMIC_RELAXED, __HIP_MEMORY_SCOPE_AGENT); }
; __device__ __forceinline__ unsigned xb_add(unsigned* p, unsigned v) { return __hip_atomic_fetch_add(p, v, __ATOMIC_RELAXED, __HIP_MEMORY_SCOPE_AGENT); }
; #define XB_SPIN(cond, bar) do { unsigned _sp = 0; while (cond) { __builtin_amdgcn_s_sleep(1); \
;     if ((++_sp & 255u) == 0u) { if (xb_ld(&(bar)[XB_TMO])) break; if (_sp > XB_SPIN_CAP) { atomicAdd(&(bar)[XB_TMO], 1u); break; } } } } while (0)
; __device__ __forceinline__ void xcd_barrier(const XcdBarrier& b, int wave_id) {
;     ...
;             const unsigned og = xb_add(&bar[XB_TOP], 1u);
;             const unsigned tg = og / nx;
;             if (og + 1u == (tg + 1u) * nx) xb_add(&bar[XB_TOPGEN], 1u);
;             else XB_SPIN(xb_ld(&bar[XB_TOPGEN]) == tg, bar);
.LBB0_767:
	s_or_b64 exec, exec, s[18:19]
	v_cvt_f32_u32_e32 v3, v0
	s_waitcnt vmcnt(0)
	v_readfirstlane_b32 s3, v2
	s_add_u32 s18, s14, 0xff43500
	s_addc_u32 s19, s15, 0
	v_rcp_iflag_f32_e32 v3, v3
	v_add_u32_e32 v1, s3, v1
	v_add_u32_e32 v4, 1, v1
	s_mov_b64 s[20:21], -1
	v_mul_f32_e32 v2, 0x4f7ffffe, v3
	v_cvt_u32_f32_e32 v2, v2
	v_sub_u32_e32 v3, 0, v0
	v_mul_lo_u32 v3, v3, v2
	v_mul_hi_u32 v3, v2, v3
	v_add_u32_e32 v2, v2, v3
	v_mul_hi_u32 v2, v1, v2
	v_mul_lo_u32 v3, v2, v0
	v_sub_u32_e32 v1, v1, v3
	v_add_u32_e32 v5, 1, v2
	v_cmp_ge_u32_e32 vcc, v1, v0
	v_sub_u32_e32 v3, v1, v0
	s_nop 0
	v_cndmask_b32_e32 v2, v2, v5, vcc
	v_cndmask_b32_e32 v1, v1, v3, vcc
	v_add_u32_e32 v3, 1, v2
	v_cmp_ge_u32_e32 vcc, v1, v0
	s_nop 1
	v_cndmask_b32_e32 v2, v2, v3, vcc
	v_mul_lo_u32 v1, v0, v2
	v_add_u32_e32 v0, v1, v0
	v_mov_b32_e32 v2, v0
	v_cmp_ne_u32_e32 vcc, v4, v0
	v_mov_b64_e32 v[0:1], s[18:19]
	s_and_saveexec_b64 s[16:17], vcc
	s_cbranch_execz .LBB0_779
	v_mov_b32_e32 v0, 0
	global_load_dword v1, v0, s[18:19] offset:-256 sc1
	s_mov_b64 s[26:27], 0
	s_waitcnt vmcnt(0)
	v_cmp_lt_u32_e32 vcc, v1, v2
	s_and_saveexec_b64 s[22:23], vcc
	s_cbranch_execz .LBB0_778
	s_add_u32 s20, s14, 0xff40200
	s_addc_u32 s21, s15, 0
	s_mov_b32 s3, 1
	s_mov_b64 s[14:15], 0
	s_branch .LBB0_771

.LBB0_773:
	global_load_dword v1, v0, s[18:19] offset:-256 sc1
	s_add_i32 s3, s3, 1
	s_mov_b64 s[28:29], -1
	s_waitcnt vmcnt(0)
	v_cmp_ge_u32_e32 vcc, v1, v2
	s_orn2_b64 s[34:35], vcc, exec
	s_branch .LBB0_770
